# scan loader loop: weight-copy transpose in registers with v_permlane32_swap instead of an LDS tile
# speedup vs baseline: 1.0024x; 1.0024x over previous
.LBB0_621:
	s_and_b32 s6, s56, 0x400
	v_lshl_add_u32 v1, s6, 2, v191
	ds_read_b128 v[72:75], v1
	v_add_u32_e32 v76, s38, v164
	v_ashrrev_i32_e32 v77, 31, v76
	v_lshlrev_b64 v[76:77], 13, v[76:77]
	v_lshl_add_u64 v[76:77], v[138:139], 0, v[76:77]
	s_andn2_b64 vcc, exec, s[8:9]
	s_waitcnt lgkmcnt(0)
	global_store_dwordx4 v[76:77], v[72:75], off
	s_cbranch_vccnz .LBB0_623
	v_readfirstlane_b32 s98, v217
	v_readfirstlane_b32 s99, v218
	s_nop 1
	s_lshr_b32 s99, s99, 5
	s_ff1_i32_b32 s100, s99
	s_add_i32 s101, s99, -1
	s_and_b32 s101, s98, s101
	s_lshr_b32 s98, s98, s100
	s_lshl_b32 s101, s101, 5
	s_lshl_b32 s98, s98, 6
	v_add_u32_e32 v1, s101, v110
	v_mul_lo_u32 v88, v1, v219
	v_lshl_add_u32 v1, v189, 5, s98
	v_add_u32_e32 v88, v88, v1
	v_mov_b32_e32 v89, 0
	v_lshl_add_u64 v[88:89], v[88:89], 1, v[132:133]
	s_waitcnt vmcnt(16)
	v_permlane32_swap_b32_e32 v4, v20
	v_cvt_pk_bf16_f32 v72, v4, v20
	s_waitcnt vmcnt(15)
	v_permlane32_swap_b32_e32 v5, v21
	v_cvt_pk_bf16_f32 v73, v5, v21
	s_waitcnt vmcnt(14)
	v_permlane32_swap_b32_e32 v6, v22
	v_cvt_pk_bf16_f32 v74, v6, v22
	s_waitcnt vmcnt(13)
	v_permlane32_swap_b32_e32 v7, v23
	v_cvt_pk_bf16_f32 v75, v7, v23
	global_store_dwordx4 v[88:89], v[72:75], off
	s_waitcnt vmcnt(12)
	v_permlane32_swap_b32_e32 v8, v24
	v_cvt_pk_bf16_f32 v76, v8, v24
	s_waitcnt vmcnt(11)
	v_permlane32_swap_b32_e32 v9, v25
	v_cvt_pk_bf16_f32 v77, v9, v25
	s_waitcnt vmcnt(10)
	v_permlane32_swap_b32_e32 v10, v26
	v_cvt_pk_bf16_f32 v78, v10, v26
	s_waitcnt vmcnt(9)
	v_permlane32_swap_b32_e32 v11, v27
	v_cvt_pk_bf16_f32 v79, v11, v27
	global_store_dwordx4 v[88:89], v[76:79], off offset:16
	s_waitcnt vmcnt(8)
	v_permlane32_swap_b32_e32 v12, v28
	v_cvt_pk_bf16_f32 v80, v12, v28
	s_waitcnt vmcnt(7)
	v_permlane32_swap_b32_e32 v13, v29
	v_cvt_pk_bf16_f32 v81, v13, v29
	s_waitcnt vmcnt(6)
	v_permlane32_swap_b32_e32 v14, v30
	v_cvt_pk_bf16_f32 v82, v14, v30
	s_waitcnt vmcnt(5)
	v_permlane32_swap_b32_e32 v15, v31
	v_cvt_pk_bf16_f32 v83, v15, v31
	global_store_dwordx4 v[88:89], v[80:83], off offset:32
	s_waitcnt vmcnt(4)
	v_permlane32_swap_b32_e32 v16, v32
	v_cvt_pk_bf16_f32 v84, v16, v32
	s_waitcnt vmcnt(3)
	v_permlane32_swap_b32_e32 v17, v33
	v_cvt_pk_bf16_f32 v85, v17, v33
	s_waitcnt vmcnt(2)
	v_permlane32_swap_b32_e32 v18, v34
	v_cvt_pk_bf16_f32 v86, v18, v34
	s_waitcnt vmcnt(1)
	v_permlane32_swap_b32_e32 v19, v35
	v_cvt_pk_bf16_f32 v87, v19, v35
	global_store_dwordx4 v[88:89], v[84:87], off offset:48
